# v40 plus GEMM accumulator zero-init moved from the unit top into the first K-iteration's load segments (overlaps partner MFMA)
# speedup vs baseline: 1.0105x; 1.0105x over previous
.LBB0_137:
	s_ashr_i32 s45, s44, 31
	s_lshl_b64 s[2:3], s[44:45], 19
	s_add_u32 s46, s24, s2
	s_addc_u32 s47, s25, s3
	s_and_b64 s[2:3], s[38:39], exec
	s_cselect_b32 s45, s47, s55
	s_cselect_b32 s60, s46, s54
	s_ashr_i32 s43, s42, 31
	s_lshl_b64 s[2:3], s[42:43], 19
	s_add_u32 s48, s30, s2
	s_addc_u32 s49, s31, s3
	s_and_b64 s[2:3], s[38:39], exec
	s_cselect_b32 s43, s49, s53
	s_cselect_b32 s61, s48, s52
	s_add_u32 s62, s52, 0x100
	s_addc_u32 s63, s53, 0
	s_add_u32 s52, s54, 0x40080
	s_addc_u32 s53, s55, 0
	s_mov_b32 s54, -2
.LBB0_138:
	s_add_u32 s2, s52, 0xfffc0080
	s_addc_u32 s3, s53, -1
	s_add_i32 s55, 0, 0x10000
	s_cmp_eq_u32 s54, 12
	s_cselect_b32 s5, s45, s3
	s_cselect_b32 s4, s60, s2
	s_cselect_b32 s3, s43, s63
	s_cselect_b32 s2, s61, s62
	s_add_i32 s66, 0, 0x14000
	v_add_u32_e32 v188, s55, v147
	v_add_u32_e32 v204, s66, v147
	ds_read_b128 v[162:165], v188
	ds_read_b128 v[166:169], v188 offset:1024
	ds_read_b128 v[184:187], v188 offset:2048
	ds_read_b128 v[188:191], v188 offset:3072
	ds_read_b128 v[192:195], v204
	ds_read_b128 v[196:199], v204 offset:1024
	ds_read_b128 v[200:203], v204 offset:2048
	ds_read_b128 v[204:207], v204 offset:3072
	v_lshl_add_u64 v[244:245], s[52:53], 0, v[138:139]
	s_add_i32 m0, s10, 0xc000
	ds_read_b128 v[208:211], v161
	ds_read_b128 v[212:215], v161 offset:1024
	ds_read_b128 v[216:219], v161 offset:2048
	ds_read_b128 v[224:227], v161 offset:3072
	ds_read_b128 v[228:231], v161 offset:4096
	ds_read_b128 v[232:235], v161 offset:5120
	ds_read_b128 v[236:239], v161 offset:6144
	ds_read_b128 v[240:243], v161 offset:7168
	global_load_lds_dwordx4 v[244:245], off
	v_lshl_add_u64 v[244:245], s[52:53], 0, v[136:137]
	s_add_i32 m0, s10, 0xe000
	s_nop 0
	global_load_lds_dwordx4 v[244:245], off
	s_cmp_lg_u32 s54, 0xfffffffe
	s_cbranch_scc1 .Lz0_0
	v_mov_b32_e32 v66, 0
	v_mov_b32_e32 v67, 0
	v_mov_b32_e32 v68, 0
	v_mov_b32_e32 v69, 0
	v_mov_b32_e32 v70, 0
	v_mov_b32_e32 v71, 0
	v_mov_b32_e32 v72, 0
	v_mov_b32_e32 v73, 0
	v_mov_b32_e32 v74, 0
	v_mov_b32_e32 v75, 0
	v_mov_b32_e32 v76, 0
	v_mov_b32_e32 v77, 0
	v_mov_b32_e32 v78, 0
	v_mov_b32_e32 v79, 0
	v_mov_b32_e32 v80, 0
	v_mov_b32_e32 v81, 0
	v_mov_b32_e32 v82, 0
	v_mov_b32_e32 v83, 0
	v_mov_b32_e32 v84, 0
	v_mov_b32_e32 v85, 0
	v_mov_b32_e32 v86, 0
	v_mov_b32_e32 v87, 0
	v_mov_b32_e32 v88, 0
	v_mov_b32_e32 v89, 0
	v_mov_b32_e32 v90, 0
	v_mov_b32_e32 v91, 0
	v_mov_b32_e32 v92, 0
	v_mov_b32_e32 v93, 0
	v_mov_b32_e32 v94, 0
	v_mov_b32_e32 v95, 0
	v_mov_b32_e32 v96, 0
	v_mov_b32_e32 v97, 0
	v_mov_b32_e32 v98, 0
	v_mov_b32_e32 v99, 0
	v_mov_b32_e32 v100, 0
	v_mov_b32_e32 v101, 0
	v_mov_b32_e32 v102, 0
	v_mov_b32_e32 v103, 0
	v_mov_b32_e32 v104, 0
	v_mov_b32_e32 v105, 0
	v_mov_b32_e32 v106, 0
	v_mov_b32_e32 v107, 0
	v_mov_b32_e32 v108, 0
	v_mov_b32_e32 v109, 0
	v_mov_b32_e32 v110, 0
	v_mov_b32_e32 v111, 0
	v_mov_b32_e32 v112, 0
	v_mov_b32_e32 v113, 0
	v_mov_b32_e32 v114, 0
	v_mov_b32_e32 v115, 0
	v_mov_b32_e32 v116, 0
	v_mov_b32_e32 v117, 0
	v_mov_b32_e32 v118, 0
	v_mov_b32_e32 v119, 0
	v_mov_b32_e32 v120, 0
	v_mov_b32_e32 v121, 0
	v_mov_b32_e32 v122, 0
	v_mov_b32_e32 v123, 0
	v_mov_b32_e32 v124, 0
	v_mov_b32_e32 v125, 0
	v_mov_b32_e32 v126, 0
	v_mov_b32_e32 v127, 0
	v_mov_b32_e32 v128, 0
	v_mov_b32_e32 v129, 0
.Lz0_0:
	s_waitcnt vmcnt(8)
	s_waitcnt lgkmcnt(0)
	s_barrier
	s_setprio 1
	s_waitcnt lgkmcnt(0)
	v_mfma_f32_16x16x32_bf16 v[126:129], v[162:165], v[208:211], v[126:129]
	v_mfma_f32_16x16x32_bf16 v[122:125], v[184:187], v[208:211], v[122:125]
	v_mfma_f32_16x16x32_bf16 v[110:113], v[162:165], v[216:219], v[110:113]
	v_mfma_f32_16x16x32_bf16 v[106:109], v[184:187], v[216:219], v[106:109]
	v_mfma_f32_16x16x32_bf16 v[94:97], v[162:165], v[228:231], v[94:97]
	v_mfma_f32_16x16x32_bf16 v[90:93], v[184:187], v[228:231], v[90:93]
	v_mfma_f32_16x16x32_bf16 v[78:81], v[162:165], v[236:239], v[78:81]
	v_mfma_f32_16x16x32_bf16 v[74:77], v[184:187], v[236:239], v[74:77]
	v_mfma_f32_16x16x32_bf16 v[126:129], v[166:169], v[212:215], v[126:129]
	v_mfma_f32_16x16x32_bf16 v[122:125], v[188:191], v[212:215], v[122:125]
	v_mfma_f32_16x16x32_bf16 v[110:113], v[166:169], v[224:227], v[110:113]
	v_mfma_f32_16x16x32_bf16 v[106:109], v[188:191], v[224:227], v[106:109]
	v_mfma_f32_16x16x32_bf16 v[94:97], v[166:169], v[232:235], v[94:97]
	v_mfma_f32_16x16x32_bf16 v[90:93], v[188:191], v[232:235], v[90:93]
	v_mfma_f32_16x16x32_bf16 v[78:81], v[166:169], v[240:243], v[78:81]
	v_mfma_f32_16x16x32_bf16 v[74:77], v[188:191], v[240:243], v[74:77]
	s_setprio 0
	s_setprio 1
	v_mfma_f32_16x16x32_bf16 v[118:121], v[192:195], v[208:211], v[118:121]
	v_mfma_f32_16x16x32_bf16 v[114:117], v[200:203], v[208:211], v[114:117]
	v_mfma_f32_16x16x32_bf16 v[102:105], v[192:195], v[216:219], v[102:105]
	v_mfma_f32_16x16x32_bf16 v[98:101], v[200:203], v[216:219], v[98:101]
	v_mfma_f32_16x16x32_bf16 v[86:89], v[192:195], v[228:231], v[86:89]
	v_mfma_f32_16x16x32_bf16 v[82:85], v[200:203], v[228:231], v[82:85]
	v_mfma_f32_16x16x32_bf16 v[70:73], v[192:195], v[236:239], v[70:73]
	v_mfma_f32_16x16x32_bf16 v[66:69], v[200:203], v[236:239], v[66:69]
	v_mfma_f32_16x16x32_bf16 v[118:121], v[196:199], v[212:215], v[118:121]
	v_mfma_f32_16x16x32_bf16 v[114:117], v[204:207], v[212:215], v[114:117]
	v_mfma_f32_16x16x32_bf16 v[102:105], v[196:199], v[224:227], v[102:105]
	v_mfma_f32_16x16x32_bf16 v[98:101], v[204:207], v[224:227], v[98:101]
	v_mfma_f32_16x16x32_bf16 v[86:89], v[196:199], v[232:235], v[86:89]
	v_mfma_f32_16x16x32_bf16 v[82:85], v[204:207], v[232:235], v[82:85]
	v_mfma_f32_16x16x32_bf16 v[70:73], v[196:199], v[240:243], v[70:73]
	v_mfma_f32_16x16x32_bf16 v[66:69], v[204:207], v[240:243], v[66:69]
	s_setprio 0
	s_barrier
	s_add_i32 s55, s55, s6
	v_lshl_add_u64 v[244:245], s[2:3], 0, v[0:1]
	s_mov_b32 m0, s55
	ds_read_b128 v[208:211], v161 offset:16384
	ds_read_b128 v[212:215], v161 offset:17408
	ds_read_b128 v[216:219], v161 offset:18432
	ds_read_b128 v[224:227], v161 offset:19456
	ds_read_b128 v[228:231], v161 offset:20480
	ds_read_b128 v[232:235], v161 offset:21504
	ds_read_b128 v[236:239], v161 offset:22528
	ds_read_b128 v[240:243], v161 offset:23552
	global_load_lds_dwordx4 v[244:245], off
	s_add_i32 m0, s55, 0x2000
	s_add_u32 s64, s2, 0x40000
	v_lshl_add_u64 v[246:247], s[2:3], 0, v[130:131]
	s_addc_u32 s65, s3, 0
	s_add_i32 s55, s66, s6
	global_load_lds_dwordx4 v[246:247], off
	v_lshl_add_u64 v[248:249], s[64:65], 0, v[0:1]
	s_mov_b32 m0, s55
	v_lshl_add_u64 v[250:251], s[4:5], 0, v[132:133]
	global_load_lds_dwordx4 v[248:249], off
	v_lshl_add_u64 v[248:249], s[64:65], 0, v[130:131]
	s_add_i32 m0, s55, 0x2000
	s_nop 0
	global_load_lds_dwordx4 v[248:249], off
	v_lshl_add_u64 v[248:249], s[4:5], 0, v[134:135]
	s_mov_b32 m0, s10
	s_nop 0
	global_load_lds_dwordx4 v[248:249], off
	s_mov_b32 m0, s11
	s_nop 0
	global_load_lds_dwordx4 v[250:251], off
	s_cmp_lg_u32 s54, 0xfffffffe
	s_cbranch_scc1 .Lz1_0
	v_mov_b32_e32 v2, 0
	v_mov_b32_e32 v3, 0
	v_mov_b32_e32 v4, 0
	v_mov_b32_e32 v5, 0
	v_mov_b32_e32 v6, 0
	v_mov_b32_e32 v7, 0
	v_mov_b32_e32 v8, 0
	v_mov_b32_e32 v9, 0
	v_mov_b32_e32 v10, 0
	v_mov_b32_e32 v11, 0
	v_mov_b32_e32 v12, 0
	v_mov_b32_e32 v13, 0
	v_mov_b32_e32 v14, 0
	v_mov_b32_e32 v15, 0
	v_mov_b32_e32 v16, 0
	v_mov_b32_e32 v17, 0
	v_mov_b32_e32 v18, 0
	v_mov_b32_e32 v19, 0
	v_mov_b32_e32 v20, 0
	v_mov_b32_e32 v21, 0
	v_mov_b32_e32 v22, 0
	v_mov_b32_e32 v23, 0
	v_mov_b32_e32 v24, 0
	v_mov_b32_e32 v25, 0
	v_mov_b32_e32 v26, 0
	v_mov_b32_e32 v27, 0
	v_mov_b32_e32 v28, 0
	v_mov_b32_e32 v29, 0
	v_mov_b32_e32 v30, 0
	v_mov_b32_e32 v31, 0
	v_mov_b32_e32 v32, 0
	v_mov_b32_e32 v33, 0
	v_mov_b32_e32 v34, 0
	v_mov_b32_e32 v35, 0
	v_mov_b32_e32 v36, 0
	v_mov_b32_e32 v37, 0
	v_mov_b32_e32 v38, 0
	v_mov_b32_e32 v39, 0
	v_mov_b32_e32 v40, 0
	v_mov_b32_e32 v41, 0
	v_mov_b32_e32 v42, 0
	v_mov_b32_e32 v43, 0
	v_mov_b32_e32 v44, 0
	v_mov_b32_e32 v45, 0
	v_mov_b32_e32 v46, 0
	v_mov_b32_e32 v47, 0
	v_mov_b32_e32 v48, 0
	v_mov_b32_e32 v49, 0
	v_mov_b32_e32 v50, 0
	v_mov_b32_e32 v51, 0
	v_mov_b32_e32 v52, 0
	v_mov_b32_e32 v53, 0
	v_mov_b32_e32 v54, 0
	v_mov_b32_e32 v55, 0
	v_mov_b32_e32 v56, 0
	v_mov_b32_e32 v57, 0
	v_mov_b32_e32 v58, 0
	v_mov_b32_e32 v59, 0
	v_mov_b32_e32 v60, 0
	v_mov_b32_e32 v61, 0
	v_mov_b32_e32 v62, 0
	v_mov_b32_e32 v63, 0
	v_mov_b32_e32 v64, 0
	v_mov_b32_e32 v65, 0
.Lz1_0:
	s_waitcnt vmcnt(8)
	s_waitcnt lgkmcnt(0)
	s_barrier
	s_setprio 1
	s_waitcnt lgkmcnt(0)
	v_mfma_f32_16x16x32_bf16 v[62:65], v[162:165], v[208:211], v[62:65]
	v_mfma_f32_16x16x32_bf16 v[58:61], v[184:187], v[208:211], v[58:61]
	v_mfma_f32_16x16x32_bf16 v[46:49], v[162:165], v[216:219], v[46:49]
	v_mfma_f32_16x16x32_bf16 v[42:45], v[184:187], v[216:219], v[42:45]
	v_mfma_f32_16x16x32_bf16 v[30:33], v[162:165], v[228:231], v[30:33]
	v_mfma_f32_16x16x32_bf16 v[26:29], v[184:187], v[228:231], v[26:29]
	v_mfma_f32_16x16x32_bf16 v[14:17], v[162:165], v[236:239], v[14:17]
	v_mfma_f32_16x16x32_bf16 v[10:13], v[184:187], v[236:239], v[10:13]
	v_mfma_f32_16x16x32_bf16 v[62:65], v[166:169], v[212:215], v[62:65]
	v_mfma_f32_16x16x32_bf16 v[58:61], v[188:191], v[212:215], v[58:61]
	v_mfma_f32_16x16x32_bf16 v[46:49], v[166:169], v[224:227], v[46:49]
	v_mfma_f32_16x16x32_bf16 v[42:45], v[188:191], v[224:227], v[42:45]
	v_mfma_f32_16x16x32_bf16 v[30:33], v[166:169], v[232:235], v[30:33]
	v_mfma_f32_16x16x32_bf16 v[26:29], v[188:191], v[232:235], v[26:29]
	v_mfma_f32_16x16x32_bf16 v[14:17], v[166:169], v[240:243], v[14:17]
	v_mfma_f32_16x16x32_bf16 v[10:13], v[188:191], v[240:243], v[10:13]
	s_setprio 0
	s_setprio 1
	v_mfma_f32_16x16x32_bf16 v[54:57], v[192:195], v[208:211], v[54:57]
	v_mfma_f32_16x16x32_bf16 v[50:53], v[200:203], v[208:211], v[50:53]
	v_mfma_f32_16x16x32_bf16 v[38:41], v[192:195], v[216:219], v[38:41]
	v_mfma_f32_16x16x32_bf16 v[34:37], v[200:203], v[216:219], v[34:37]
	v_mfma_f32_16x16x32_bf16 v[22:25], v[192:195], v[228:231], v[22:25]
	v_mfma_f32_16x16x32_bf16 v[18:21], v[200:203], v[228:231], v[18:21]
	v_mfma_f32_16x16x32_bf16 v[6:9], v[192:195], v[236:239], v[6:9]
	v_mfma_f32_16x16x32_bf16 v[2:5], v[200:203], v[236:239], v[2:5]
	v_mfma_f32_16x16x32_bf16 v[54:57], v[196:199], v[212:215], v[54:57]
	v_mfma_f32_16x16x32_bf16 v[50:53], v[204:207], v[212:215], v[50:53]
	v_mfma_f32_16x16x32_bf16 v[38:41], v[196:199], v[224:227], v[38:41]
	v_mfma_f32_16x16x32_bf16 v[34:37], v[204:207], v[224:227], v[34:37]
	v_mfma_f32_16x16x32_bf16 v[22:25], v[196:199], v[232:235], v[22:25]
	v_mfma_f32_16x16x32_bf16 v[18:21], v[204:207], v[232:235], v[18:21]
	v_mfma_f32_16x16x32_bf16 v[6:9], v[196:199], v[240:243], v[6:9]
	v_mfma_f32_16x16x32_bf16 v[2:5], v[204:207], v[240:243], v[2:5]
	s_setprio 0
	s_barrier
	s_add_i32 s55, 0, 0x18000
	s_add_i32 s64, 0, 0x1c000
	v_add_u32_e32 v188, s55, v147
	v_add_u32_e32 v204, s64, v147
	ds_read_b128 v[162:165], v188
	ds_read_b128 v[166:169], v188 offset:1024
	ds_read_b128 v[184:187], v188 offset:2048
	ds_read_b128 v[188:191], v188 offset:3072
	ds_read_b128 v[192:195], v204
	ds_read_b128 v[196:199], v204 offset:1024
	ds_read_b128 v[200:203], v204 offset:2048
	ds_read_b128 v[204:207], v204 offset:3072
	s_add_u32 s4, s4, 0x40000
	s_addc_u32 s5, s5, 0
	s_mov_b32 m0, s36
	v_lshl_add_u64 v[252:253], s[4:5], 0, v[134:135]
	ds_read_b128 v[208:211], v161 offset:32768
	ds_read_b128 v[212:215], v161 offset:33792
	ds_read_b128 v[216:219], v161 offset:34816
	ds_read_b128 v[224:227], v161 offset:35840
	ds_read_b128 v[228:231], v161 offset:36864
	ds_read_b128 v[232:235], v161 offset:37888
	ds_read_b128 v[236:239], v161 offset:38912
	ds_read_b128 v[240:243], v161 offset:39936
	global_load_lds_dwordx4 v[252:253], off
	v_lshl_add_u64 v[252:253], s[4:5], 0, v[132:133]
	s_mov_b32 m0, s37
	s_nop 0
	global_load_lds_dwordx4 v[252:253], off
	s_waitcnt vmcnt(8)
	s_waitcnt lgkmcnt(0)
	s_barrier
	s_setprio 1
	s_waitcnt lgkmcnt(0)
	v_mfma_f32_16x16x32_bf16 v[126:129], v[162:165], v[208:211], v[126:129]
	v_mfma_f32_16x16x32_bf16 v[122:125], v[184:187], v[208:211], v[122:125]
	v_mfma_f32_16x16x32_bf16 v[110:113], v[162:165], v[216:219], v[110:113]
	v_mfma_f32_16x16x32_bf16 v[106:109], v[184:187], v[216:219], v[106:109]
	v_mfma_f32_16x16x32_bf16 v[94:97], v[162:165], v[228:231], v[94:97]
	v_mfma_f32_16x16x32_bf16 v[90:93], v[184:187], v[228:231], v[90:93]
	v_mfma_f32_16x16x32_bf16 v[78:81], v[162:165], v[236:239], v[78:81]
	v_mfma_f32_16x16x32_bf16 v[74:77], v[184:187], v[236:239], v[74:77]
	v_mfma_f32_16x16x32_bf16 v[126:129], v[166:169], v[212:215], v[126:129]
	v_mfma_f32_16x16x32_bf16 v[122:125], v[188:191], v[212:215], v[122:125]
	v_mfma_f32_16x16x32_bf16 v[110:113], v[166:169], v[224:227], v[110:113]
	v_mfma_f32_16x16x32_bf16 v[106:109], v[188:191], v[224:227], v[106:109]
	v_mfma_f32_16x16x32_bf16 v[94:97], v[166:169], v[232:235], v[94:97]
	v_mfma_f32_16x16x32_bf16 v[90:93], v[188:191], v[232:235], v[90:93]
	v_mfma_f32_16x16x32_bf16 v[78:81], v[166:169], v[240:243], v[78:81]
	v_mfma_f32_16x16x32_bf16 v[74:77], v[188:191], v[240:243], v[74:77]
	s_setprio 0
	s_setprio 1
	v_mfma_f32_16x16x32_bf16 v[118:121], v[192:195], v[208:211], v[118:121]
	v_mfma_f32_16x16x32_bf16 v[114:117], v[200:203], v[208:211], v[114:117]
	v_mfma_f32_16x16x32_bf16 v[102:105], v[192:195], v[216:219], v[102:105]
	v_mfma_f32_16x16x32_bf16 v[98:101], v[200:203], v[216:219], v[98:101]
	v_mfma_f32_16x16x32_bf16 v[86:89], v[192:195], v[228:231], v[86:89]
	v_mfma_f32_16x16x32_bf16 v[82:85], v[200:203], v[228:231], v[82:85]
	v_mfma_f32_16x16x32_bf16 v[70:73], v[192:195], v[236:239], v[70:73]
	v_mfma_f32_16x16x32_bf16 v[66:69], v[200:203], v[236:239], v[66:69]
	v_mfma_f32_16x16x32_bf16 v[118:121], v[196:199], v[212:215], v[118:121]
	v_mfma_f32_16x16x32_bf16 v[114:117], v[204:207], v[212:215], v[114:117]
	v_mfma_f32_16x16x32_bf16 v[102:105], v[196:199], v[224:227], v[102:105]
	v_mfma_f32_16x16x32_bf16 v[98:101], v[204:207], v[224:227], v[98:101]
	v_mfma_f32_16x16x32_bf16 v[86:89], v[196:199], v[232:235], v[86:89]
	v_mfma_f32_16x16x32_bf16 v[82:85], v[204:207], v[232:235], v[82:85]
	v_mfma_f32_16x16x32_bf16 v[70:73], v[196:199], v[240:243], v[70:73]
	v_mfma_f32_16x16x32_bf16 v[66:69], v[204:207], v[240:243], v[66:69]
	s_setprio 0
	s_barrier
	s_add_i32 s4, s55, s6
	v_lshl_add_u64 v[244:245], v[244:245], 0, s[12:13]
	s_mov_b32 m0, s4
	ds_read_b128 v[208:211], v161 offset:49152
	ds_read_b128 v[212:215], v161 offset:50176
	ds_read_b128 v[216:219], v161 offset:51200
	ds_read_b128 v[224:227], v161 offset:52224
	ds_read_b128 v[228:231], v161 offset:53248
	ds_read_b128 v[232:235], v161 offset:54272
	ds_read_b128 v[236:239], v161 offset:55296
	ds_read_b128 v[240:243], v161 offset:56320
	global_load_lds_dwordx4 v[244:245], off
	s_add_i32 m0, s4, 0x2000
	s_add_u32 s2, s2, 0x40080
	v_lshl_add_u64 v[244:245], v[246:247], 0, s[12:13]
	s_addc_u32 s3, s3, 0
	s_add_i32 s4, s64, s6
	global_load_lds_dwordx4 v[244:245], off
	v_lshl_add_u64 v[244:245], s[2:3], 0, v[0:1]
	s_mov_b32 m0, s4
	s_nop 0
	global_load_lds_dwordx4 v[244:245], off
	v_lshl_add_u64 v[244:245], s[2:3], 0, v[130:131]
	s_add_i32 m0, s4, 0x2000
	s_nop 0
	global_load_lds_dwordx4 v[244:245], off
	v_lshl_add_u64 v[244:245], v[248:249], 0, s[12:13]
	s_mov_b32 m0, s56
	s_nop 0
	global_load_lds_dwordx4 v[244:245], off
	v_lshl_add_u64 v[244:245], v[250:251], 0, s[12:13]
	s_mov_b32 m0, s57
	s_nop 0
	global_load_lds_dwordx4 v[244:245], off
	s_waitcnt vmcnt(8)
	s_waitcnt lgkmcnt(0)
	s_barrier
	s_setprio 1
	s_waitcnt lgkmcnt(0)
	v_mfma_f32_16x16x32_bf16 v[62:65], v[162:165], v[208:211], v[62:65]
	v_mfma_f32_16x16x32_bf16 v[58:61], v[184:187], v[208:211], v[58:61]
	v_mfma_f32_16x16x32_bf16 v[46:49], v[162:165], v[216:219], v[46:49]
	v_mfma_f32_16x16x32_bf16 v[42:45], v[184:187], v[216:219], v[42:45]
	v_mfma_f32_16x16x32_bf16 v[30:33], v[162:165], v[228:231], v[30:33]
	v_mfma_f32_16x16x32_bf16 v[26:29], v[184:187], v[228:231], v[26:29]
	v_mfma_f32_16x16x32_bf16 v[14:17], v[162:165], v[236:239], v[14:17]
	v_mfma_f32_16x16x32_bf16 v[10:13], v[184:187], v[236:239], v[10:13]
	v_mfma_f32_16x16x32_bf16 v[62:65], v[166:169], v[212:215], v[62:65]
	v_mfma_f32_16x16x32_bf16 v[58:61], v[188:191], v[212:215], v[58:61]
	v_mfma_f32_16x16x32_bf16 v[46:49], v[166:169], v[224:227], v[46:49]
	v_mfma_f32_16x16x32_bf16 v[42:45], v[188:191], v[224:227], v[42:45]
	v_mfma_f32_16x16x32_bf16 v[30:33], v[166:169], v[232:235], v[30:33]
	v_mfma_f32_16x16x32_bf16 v[26:29], v[188:191], v[232:235], v[26:29]
	v_mfma_f32_16x16x32_bf16 v[14:17], v[166:169], v[240:243], v[14:17]
	v_mfma_f32_16x16x32_bf16 v[10:13], v[188:191], v[240:243], v[10:13]
	s_setprio 0
	s_setprio 1
	v_mfma_f32_16x16x32_bf16 v[54:57], v[192:195], v[208:211], v[54:57]
	v_mfma_f32_16x16x32_bf16 v[50:53], v[200:203], v[208:211], v[50:53]
	v_mfma_f32_16x16x32_bf16 v[38:41], v[192:195], v[216:219], v[38:41]
	v_mfma_f32_16x16x32_bf16 v[34:37], v[200:203], v[216:219], v[34:37]
	v_mfma_f32_16x16x32_bf16 v[22:25], v[192:195], v[228:231], v[22:25]
	v_mfma_f32_16x16x32_bf16 v[18:21], v[200:203], v[228:231], v[18:21]
	v_mfma_f32_16x16x32_bf16 v[6:9], v[192:195], v[236:239], v[6:9]
	v_mfma_f32_16x16x32_bf16 v[2:5], v[200:203], v[236:239], v[2:5]
	v_mfma_f32_16x16x32_bf16 v[54:57], v[196:199], v[212:215], v[54:57]
	v_mfma_f32_16x16x32_bf16 v[50:53], v[204:207], v[212:215], v[50:53]
	v_mfma_f32_16x16x32_bf16 v[38:41], v[196:199], v[224:227], v[38:41]
	v_mfma_f32_16x16x32_bf16 v[34:37], v[204:207], v[224:227], v[34:37]
	v_mfma_f32_16x16x32_bf16 v[22:25], v[196:199], v[232:235], v[22:25]
	v_mfma_f32_16x16x32_bf16 v[18:21], v[204:207], v[232:235], v[18:21]
	v_mfma_f32_16x16x32_bf16 v[6:9], v[196:199], v[240:243], v[6:9]
	v_mfma_f32_16x16x32_bf16 v[2:5], v[204:207], v[240:243], v[2:5]
	s_setprio 0
	s_barrier
	s_add_i32 s54, s54, 2
	s_add_u32 s62, s62, 0x100
	s_addc_u32 s63, s63, 0
	s_add_u32 s52, s52, 0x100
	s_addc_u32 s53, s53, 0
	s_cmp_gt_u32 s54, 13
	s_cbranch_scc0 .LBB0_138
	s_and_b64 vcc, exec, s[40:41]
	s_cbranch_vccz .LBB0_141
	s_barrier

.LBB0_383:
	s_add_u32 s42, s44, 0x100
	s_addc_u32 s43, s45, 0
	s_add_u32 s20, s50, 0x80
	s_addc_u32 s21, s51, 0
	s_mov_b32 s2, 0
.LBB0_384:
	s_add_i32 s44, s2, 2
	s_add_u32 s45, s20, 0x80
	s_addc_u32 s3, s21, 0
	s_add_i32 s69, 0, 0x10000
	s_cmp_eq_u32 s61, s2
	s_cselect_b32 s3, s47, s3
	s_cselect_b32 s2, s46, s45
	v_add_u32_e32 v133, s69, v147
	s_cselect_b32 s51, s49, s43
	s_cselect_b32 s50, s48, s42
	s_add_i32 s45, 0, 0x14000
	ds_read_b128 v[140:143], v133
	ds_read_b128 v[148:151], v133 offset:1024
	ds_read_b128 v[152:155], v133 offset:2048
	ds_read_b128 v[160:163], v133 offset:3072
	v_add_u32_e32 v133, s45, v147
	ds_read_b128 v[164:167], v133
	ds_read_b128 v[184:187], v133 offset:1024
	ds_read_b128 v[188:191], v133 offset:2048
	ds_read_b128 v[192:195], v133 offset:3072
	v_lshl_add_u64 v[156:157], s[20:21], 0, v[138:139]
	s_add_i32 m0, s54, 0xc000
	ds_read_b128 v[196:199], v159
	ds_read_b128 v[200:203], v159 offset:1024
	ds_read_b128 v[204:207], v159 offset:2048
	ds_read_b128 v[208:211], v159 offset:3072
	ds_read_b128 v[212:215], v159 offset:4096
	ds_read_b128 v[216:219], v159 offset:5120
	ds_read_b128 v[224:227], v159 offset:6144
	ds_read_b128 v[228:231], v159 offset:7168
	global_load_lds_dwordx4 v[156:157], off
	v_lshl_add_u64 v[156:157], s[20:21], 0, v[136:137]
	s_add_i32 m0, s54, 0xe000
	s_nop 0
	global_load_lds_dwordx4 v[156:157], off
	s_cmp_lg_u32 s44, 2
	s_cbranch_scc1 .Lz0_1
	v_mov_b32_e32 v66, 0
	v_mov_b32_e32 v67, 0
	v_mov_b32_e32 v68, 0
	v_mov_b32_e32 v69, 0
	v_mov_b32_e32 v70, 0
	v_mov_b32_e32 v71, 0
	v_mov_b32_e32 v72, 0
	v_mov_b32_e32 v73, 0
	v_mov_b32_e32 v74, 0
	v_mov_b32_e32 v75, 0
	v_mov_b32_e32 v76, 0
	v_mov_b32_e32 v77, 0
	v_mov_b32_e32 v78, 0
	v_mov_b32_e32 v79, 0
	v_mov_b32_e32 v80, 0
	v_mov_b32_e32 v81, 0
	v_mov_b32_e32 v82, 0
	v_mov_b32_e32 v83, 0
	v_mov_b32_e32 v84, 0
	v_mov_b32_e32 v85, 0
	v_mov_b32_e32 v86, 0
	v_mov_b32_e32 v87, 0
	v_mov_b32_e32 v88, 0
	v_mov_b32_e32 v89, 0
	v_mov_b32_e32 v90, 0
	v_mov_b32_e32 v91, 0
	v_mov_b32_e32 v92, 0
	v_mov_b32_e32 v93, 0
	v_mov_b32_e32 v94, 0
	v_mov_b32_e32 v95, 0
	v_mov_b32_e32 v96, 0
	v_mov_b32_e32 v97, 0
	v_mov_b32_e32 v98, 0
	v_mov_b32_e32 v99, 0
	v_mov_b32_e32 v100, 0
	v_mov_b32_e32 v101, 0
	v_mov_b32_e32 v102, 0
	v_mov_b32_e32 v103, 0
	v_mov_b32_e32 v104, 0
	v_mov_b32_e32 v105, 0
	v_mov_b32_e32 v106, 0
	v_mov_b32_e32 v107, 0
	v_mov_b32_e32 v108, 0
	v_mov_b32_e32 v109, 0
	v_mov_b32_e32 v110, 0
	v_mov_b32_e32 v111, 0
	v_mov_b32_e32 v112, 0
	v_mov_b32_e32 v113, 0
	v_mov_b32_e32 v114, 0
	v_mov_b32_e32 v115, 0
	v_mov_b32_e32 v116, 0
	v_mov_b32_e32 v117, 0
	v_mov_b32_e32 v118, 0
	v_mov_b32_e32 v119, 0
	v_mov_b32_e32 v120, 0
	v_mov_b32_e32 v121, 0
	v_mov_b32_e32 v122, 0
	v_mov_b32_e32 v123, 0
	v_mov_b32_e32 v124, 0
	v_mov_b32_e32 v125, 0
	v_mov_b32_e32 v126, 0
	v_mov_b32_e32 v127, 0
	v_mov_b32_e32 v128, 0
	v_mov_b32_e32 v129, 0
.Lz0_1:
	s_waitcnt vmcnt(8)
	s_waitcnt lgkmcnt(0)
	s_barrier
	s_setprio 1
	s_waitcnt lgkmcnt(0)
	v_mfma_f32_16x16x32_bf16 v[126:129], v[140:143], v[196:199], v[126:129]
	v_mfma_f32_16x16x32_bf16 v[122:125], v[152:155], v[196:199], v[122:125]
	v_mfma_f32_16x16x32_bf16 v[110:113], v[140:143], v[204:207], v[110:113]
	v_mfma_f32_16x16x32_bf16 v[106:109], v[152:155], v[204:207], v[106:109]
	v_mfma_f32_16x16x32_bf16 v[94:97], v[140:143], v[212:215], v[94:97]
	v_mfma_f32_16x16x32_bf16 v[90:93], v[152:155], v[212:215], v[90:93]
	v_mfma_f32_16x16x32_bf16 v[78:81], v[140:143], v[224:227], v[78:81]
	v_mfma_f32_16x16x32_bf16 v[74:77], v[152:155], v[224:227], v[74:77]
	v_mfma_f32_16x16x32_bf16 v[126:129], v[148:151], v[200:203], v[126:129]
	v_mfma_f32_16x16x32_bf16 v[122:125], v[160:163], v[200:203], v[122:125]
	v_mfma_f32_16x16x32_bf16 v[110:113], v[148:151], v[208:211], v[110:113]
	v_mfma_f32_16x16x32_bf16 v[106:109], v[160:163], v[208:211], v[106:109]
	v_mfma_f32_16x16x32_bf16 v[94:97], v[148:151], v[216:219], v[94:97]
	v_mfma_f32_16x16x32_bf16 v[90:93], v[160:163], v[216:219], v[90:93]
	v_mfma_f32_16x16x32_bf16 v[78:81], v[148:151], v[228:231], v[78:81]
	v_mfma_f32_16x16x32_bf16 v[74:77], v[160:163], v[228:231], v[74:77]
	s_setprio 0
	s_setprio 1
	v_mfma_f32_16x16x32_bf16 v[118:121], v[164:167], v[196:199], v[118:121]
	v_mfma_f32_16x16x32_bf16 v[114:117], v[188:191], v[196:199], v[114:117]
	v_mfma_f32_16x16x32_bf16 v[102:105], v[164:167], v[204:207], v[102:105]
	v_mfma_f32_16x16x32_bf16 v[98:101], v[188:191], v[204:207], v[98:101]
	v_mfma_f32_16x16x32_bf16 v[86:89], v[164:167], v[212:215], v[86:89]
	v_mfma_f32_16x16x32_bf16 v[82:85], v[188:191], v[212:215], v[82:85]
	v_mfma_f32_16x16x32_bf16 v[70:73], v[164:167], v[224:227], v[70:73]
	v_mfma_f32_16x16x32_bf16 v[66:69], v[188:191], v[224:227], v[66:69]
	v_mfma_f32_16x16x32_bf16 v[118:121], v[184:187], v[200:203], v[118:121]
	v_mfma_f32_16x16x32_bf16 v[114:117], v[192:195], v[200:203], v[114:117]
	v_mfma_f32_16x16x32_bf16 v[102:105], v[184:187], v[208:211], v[102:105]
	v_mfma_f32_16x16x32_bf16 v[98:101], v[192:195], v[208:211], v[98:101]
	v_mfma_f32_16x16x32_bf16 v[86:89], v[184:187], v[216:219], v[86:89]
	v_mfma_f32_16x16x32_bf16 v[82:85], v[192:195], v[216:219], v[82:85]
	v_mfma_f32_16x16x32_bf16 v[70:73], v[184:187], v[228:231], v[70:73]
	v_mfma_f32_16x16x32_bf16 v[66:69], v[192:195], v[228:231], v[66:69]
	s_setprio 0
	s_barrier
	s_add_i32 s69, s69, s7
	v_lshl_add_u64 v[156:157], s[50:51], 0, v[0:1]
	s_mov_b32 m0, s69
	ds_read_b128 v[196:199], v159 offset:16384
	ds_read_b128 v[200:203], v159 offset:17408
	ds_read_b128 v[204:207], v159 offset:18432
	ds_read_b128 v[208:211], v159 offset:19456
	ds_read_b128 v[212:215], v159 offset:20480
	ds_read_b128 v[216:219], v159 offset:21504
	ds_read_b128 v[224:227], v159 offset:22528
	ds_read_b128 v[228:231], v159 offset:23552
	global_load_lds_dwordx4 v[156:157], off
	s_add_i32 m0, s69, 0x2000
	v_lshl_add_u64 v[168:169], s[50:51], 0, v[130:131]
	s_add_u32 s50, s50, s80
	s_addc_u32 s51, s51, 0
	s_add_i32 s45, s45, s7
	global_load_lds_dwordx4 v[168:169], off
	v_lshl_add_u64 v[232:233], s[50:51], 0, v[0:1]
	s_mov_b32 m0, s45
	v_lshl_add_u64 v[234:235], s[50:51], 0, v[130:131]
	global_load_lds_dwordx4 v[232:233], off
	s_add_i32 m0, s45, 0x2000
	v_lshl_add_u64 v[236:237], s[2:3], 0, v[0:1]
	global_load_lds_dwordx4 v[234:235], off
	s_mov_b32 m0, s54
	v_lshl_add_u64 v[238:239], s[2:3], 0, v[130:131]
	global_load_lds_dwordx4 v[236:237], off
	s_mov_b32 m0, s55
	s_nop 0
	global_load_lds_dwordx4 v[238:239], off
	s_cmp_lg_u32 s44, 2
	s_cbranch_scc1 .Lz1_1
	v_mov_b32_e32 v2, 0
	v_mov_b32_e32 v3, 0
	v_mov_b32_e32 v4, 0
	v_mov_b32_e32 v5, 0
	v_mov_b32_e32 v6, 0
	v_mov_b32_e32 v7, 0
	v_mov_b32_e32 v8, 0
	v_mov_b32_e32 v9, 0
	v_mov_b32_e32 v10, 0
	v_mov_b32_e32 v11, 0
	v_mov_b32_e32 v12, 0
	v_mov_b32_e32 v13, 0
	v_mov_b32_e32 v14, 0
	v_mov_b32_e32 v15, 0
	v_mov_b32_e32 v16, 0
	v_mov_b32_e32 v17, 0
	v_mov_b32_e32 v18, 0
	v_mov_b32_e32 v19, 0
	v_mov_b32_e32 v20, 0
	v_mov_b32_e32 v21, 0
	v_mov_b32_e32 v22, 0
	v_mov_b32_e32 v23, 0
	v_mov_b32_e32 v24, 0
	v_mov_b32_e32 v25, 0
	v_mov_b32_e32 v26, 0
	v_mov_b32_e32 v27, 0
	v_mov_b32_e32 v28, 0
	v_mov_b32_e32 v29, 0
	v_mov_b32_e32 v30, 0
	v_mov_b32_e32 v31, 0
	v_mov_b32_e32 v32, 0
	v_mov_b32_e32 v33, 0
	v_mov_b32_e32 v34, 0
	v_mov_b32_e32 v35, 0
	v_mov_b32_e32 v36, 0
	v_mov_b32_e32 v37, 0
	v_mov_b32_e32 v38, 0
	v_mov_b32_e32 v39, 0
	v_mov_b32_e32 v40, 0
	v_mov_b32_e32 v41, 0
	v_mov_b32_e32 v42, 0
	v_mov_b32_e32 v43, 0
	v_mov_b32_e32 v44, 0
	v_mov_b32_e32 v45, 0
	v_mov_b32_e32 v46, 0
	v_mov_b32_e32 v47, 0
	v_mov_b32_e32 v48, 0
	v_mov_b32_e32 v49, 0
	v_mov_b32_e32 v50, 0
	v_mov_b32_e32 v51, 0
	v_mov_b32_e32 v52, 0
	v_mov_b32_e32 v53, 0
	v_mov_b32_e32 v54, 0
	v_mov_b32_e32 v55, 0
	v_mov_b32_e32 v56, 0
	v_mov_b32_e32 v57, 0
	v_mov_b32_e32 v58, 0
	v_mov_b32_e32 v59, 0
	v_mov_b32_e32 v60, 0
	v_mov_b32_e32 v61, 0
	v_mov_b32_e32 v62, 0
	v_mov_b32_e32 v63, 0
	v_mov_b32_e32 v64, 0
	v_mov_b32_e32 v65, 0
.Lz1_1:
	s_waitcnt vmcnt(8)
	s_waitcnt lgkmcnt(0)
	s_barrier
	s_setprio 1
	s_waitcnt lgkmcnt(0)
	v_mfma_f32_16x16x32_bf16 v[62:65], v[140:143], v[196:199], v[62:65]
	v_mfma_f32_16x16x32_bf16 v[58:61], v[152:155], v[196:199], v[58:61]
	v_mfma_f32_16x16x32_bf16 v[46:49], v[140:143], v[204:207], v[46:49]
	v_mfma_f32_16x16x32_bf16 v[42:45], v[152:155], v[204:207], v[42:45]
	v_mfma_f32_16x16x32_bf16 v[30:33], v[140:143], v[212:215], v[30:33]
	v_mfma_f32_16x16x32_bf16 v[26:29], v[152:155], v[212:215], v[26:29]
	v_mfma_f32_16x16x32_bf16 v[14:17], v[140:143], v[224:227], v[14:17]
	v_mfma_f32_16x16x32_bf16 v[10:13], v[152:155], v[224:227], v[10:13]
	v_mfma_f32_16x16x32_bf16 v[62:65], v[148:151], v[200:203], v[62:65]
	v_mfma_f32_16x16x32_bf16 v[58:61], v[160:163], v[200:203], v[58:61]
	v_mfma_f32_16x16x32_bf16 v[46:49], v[148:151], v[208:211], v[46:49]
	v_mfma_f32_16x16x32_bf16 v[42:45], v[160:163], v[208:211], v[42:45]
	v_mfma_f32_16x16x32_bf16 v[30:33], v[148:151], v[216:219], v[30:33]
	v_mfma_f32_16x16x32_bf16 v[26:29], v[160:163], v[216:219], v[26:29]
	v_mfma_f32_16x16x32_bf16 v[14:17], v[148:151], v[228:231], v[14:17]
	v_mfma_f32_16x16x32_bf16 v[10:13], v[160:163], v[228:231], v[10:13]
	s_setprio 0
	s_setprio 1
	v_mfma_f32_16x16x32_bf16 v[54:57], v[164:167], v[196:199], v[54:57]
	v_mfma_f32_16x16x32_bf16 v[50:53], v[188:191], v[196:199], v[50:53]
	v_mfma_f32_16x16x32_bf16 v[38:41], v[164:167], v[204:207], v[38:41]
	v_mfma_f32_16x16x32_bf16 v[34:37], v[188:191], v[204:207], v[34:37]
	v_mfma_f32_16x16x32_bf16 v[22:25], v[164:167], v[212:215], v[22:25]
	v_mfma_f32_16x16x32_bf16 v[18:21], v[188:191], v[212:215], v[18:21]
	v_mfma_f32_16x16x32_bf16 v[6:9], v[164:167], v[224:227], v[6:9]
	v_mfma_f32_16x16x32_bf16 v[2:5], v[188:191], v[224:227], v[2:5]
	v_mfma_f32_16x16x32_bf16 v[54:57], v[184:187], v[200:203], v[54:57]
	v_mfma_f32_16x16x32_bf16 v[50:53], v[192:195], v[200:203], v[50:53]
	v_mfma_f32_16x16x32_bf16 v[38:41], v[184:187], v[208:211], v[38:41]
	v_mfma_f32_16x16x32_bf16 v[34:37], v[192:195], v[208:211], v[34:37]
	v_mfma_f32_16x16x32_bf16 v[22:25], v[184:187], v[216:219], v[22:25]
	v_mfma_f32_16x16x32_bf16 v[18:21], v[192:195], v[216:219], v[18:21]
	v_mfma_f32_16x16x32_bf16 v[6:9], v[184:187], v[228:231], v[6:9]
	v_mfma_f32_16x16x32_bf16 v[2:5], v[192:195], v[228:231], v[2:5]
	s_setprio 0
	s_barrier
	s_add_i32 s45, 0, 0x18000
	v_add_u32_e32 v133, s45, v147
	s_add_i32 s50, 0, 0x1c000
	ds_read_b128 v[140:143], v133
	ds_read_b128 v[148:151], v133 offset:1024
	ds_read_b128 v[152:155], v133 offset:2048
	ds_read_b128 v[160:163], v133 offset:3072
	v_add_u32_e32 v133, s50, v147
	ds_read_b128 v[164:167], v133
	ds_read_b128 v[184:187], v133 offset:1024
	ds_read_b128 v[188:191], v133 offset:2048
	ds_read_b128 v[192:195], v133 offset:3072
	s_add_u32 s2, s2, s80
	s_addc_u32 s3, s3, 0
	s_mov_b32 m0, s56
	v_lshl_add_u64 v[240:241], s[2:3], 0, v[0:1]
	ds_read_b128 v[196:199], v159 offset:32768
	ds_read_b128 v[200:203], v159 offset:33792
	ds_read_b128 v[204:207], v159 offset:34816
	ds_read_b128 v[208:211], v159 offset:35840
	ds_read_b128 v[212:215], v159 offset:36864
	ds_read_b128 v[216:219], v159 offset:37888
	ds_read_b128 v[224:227], v159 offset:38912
	ds_read_b128 v[228:231], v159 offset:39936
	global_load_lds_dwordx4 v[240:241], off
	v_lshl_add_u64 v[240:241], s[2:3], 0, v[130:131]
	s_mov_b32 m0, s57
	s_nop 0
	global_load_lds_dwordx4 v[240:241], off
	s_waitcnt vmcnt(8)
	s_waitcnt lgkmcnt(0)
	s_barrier
	s_setprio 1
	s_waitcnt lgkmcnt(0)
	v_mfma_f32_16x16x32_bf16 v[126:129], v[140:143], v[196:199], v[126:129]
	v_mfma_f32_16x16x32_bf16 v[122:125], v[152:155], v[196:199], v[122:125]
	v_mfma_f32_16x16x32_bf16 v[110:113], v[140:143], v[204:207], v[110:113]
	v_mfma_f32_16x16x32_bf16 v[106:109], v[152:155], v[204:207], v[106:109]
	v_mfma_f32_16x16x32_bf16 v[94:97], v[140:143], v[212:215], v[94:97]
	v_mfma_f32_16x16x32_bf16 v[90:93], v[152:155], v[212:215], v[90:93]
	v_mfma_f32_16x16x32_bf16 v[78:81], v[140:143], v[224:227], v[78:81]
	v_mfma_f32_16x16x32_bf16 v[74:77], v[152:155], v[224:227], v[74:77]
	v_mfma_f32_16x16x32_bf16 v[126:129], v[148:151], v[200:203], v[126:129]
	v_mfma_f32_16x16x32_bf16 v[122:125], v[160:163], v[200:203], v[122:125]
	v_mfma_f32_16x16x32_bf16 v[110:113], v[148:151], v[208:211], v[110:113]
	v_mfma_f32_16x16x32_bf16 v[106:109], v[160:163], v[208:211], v[106:109]
	v_mfma_f32_16x16x32_bf16 v[94:97], v[148:151], v[216:219], v[94:97]
	v_mfma_f32_16x16x32_bf16 v[90:93], v[160:163], v[216:219], v[90:93]
	v_mfma_f32_16x16x32_bf16 v[78:81], v[148:151], v[228:231], v[78:81]
	v_mfma_f32_16x16x32_bf16 v[74:77], v[160:163], v[228:231], v[74:77]
	s_setprio 0
	s_setprio 1
	v_mfma_f32_16x16x32_bf16 v[118:121], v[164:167], v[196:199], v[118:121]
	v_mfma_f32_16x16x32_bf16 v[114:117], v[188:191], v[196:199], v[114:117]
	v_mfma_f32_16x16x32_bf16 v[102:105], v[164:167], v[204:207], v[102:105]
	v_mfma_f32_16x16x32_bf16 v[98:101], v[188:191], v[204:207], v[98:101]
	v_mfma_f32_16x16x32_bf16 v[86:89], v[164:167], v[212:215], v[86:89]
	v_mfma_f32_16x16x32_bf16 v[82:85], v[188:191], v[212:215], v[82:85]
	v_mfma_f32_16x16x32_bf16 v[70:73], v[164:167], v[224:227], v[70:73]
	v_mfma_f32_16x16x32_bf16 v[66:69], v[188:191], v[224:227], v[66:69]
	v_mfma_f32_16x16x32_bf16 v[118:121], v[184:187], v[200:203], v[118:121]
	v_mfma_f32_16x16x32_bf16 v[114:117], v[192:195], v[200:203], v[114:117]
	v_mfma_f32_16x16x32_bf16 v[102:105], v[184:187], v[208:211], v[102:105]
	v_mfma_f32_16x16x32_bf16 v[98:101], v[192:195], v[208:211], v[98:101]
	v_mfma_f32_16x16x32_bf16 v[86:89], v[184:187], v[216:219], v[86:89]
	v_mfma_f32_16x16x32_bf16 v[82:85], v[192:195], v[216:219], v[82:85]
	v_mfma_f32_16x16x32_bf16 v[70:73], v[184:187], v[228:231], v[70:73]
	v_mfma_f32_16x16x32_bf16 v[66:69], v[192:195], v[228:231], v[66:69]
	s_setprio 0
	s_barrier
	s_add_i32 s2, s45, s7
	v_lshl_add_u64 v[156:157], v[156:157], 0, s[12:13]
	s_mov_b32 m0, s2
	ds_read_b128 v[196:199], v159 offset:49152
	ds_read_b128 v[200:203], v159 offset:50176
	ds_read_b128 v[204:207], v159 offset:51200
	ds_read_b128 v[208:211], v159 offset:52224
	ds_read_b128 v[212:215], v159 offset:53248
	ds_read_b128 v[216:219], v159 offset:54272
	ds_read_b128 v[224:227], v159 offset:55296
	ds_read_b128 v[228:231], v159 offset:56320
	global_load_lds_dwordx4 v[156:157], off
	v_lshl_add_u64 v[156:157], v[168:169], 0, s[12:13]
	s_add_i32 m0, s2, 0x2000
	s_add_i32 s2, s50, s7
	global_load_lds_dwordx4 v[156:157], off
	v_lshl_add_u64 v[156:157], v[232:233], 0, s[12:13]
	s_mov_b32 m0, s2
	s_nop 0
	global_load_lds_dwordx4 v[156:157], off
	v_lshl_add_u64 v[156:157], v[234:235], 0, s[12:13]
	s_add_i32 m0, s2, 0x2000
	s_nop 0
	global_load_lds_dwordx4 v[156:157], off
	v_lshl_add_u64 v[156:157], v[236:237], 0, s[12:13]
	s_mov_b32 m0, s58
	s_nop 0
	global_load_lds_dwordx4 v[156:157], off
	v_lshl_add_u64 v[156:157], v[238:239], 0, s[12:13]
	s_mov_b32 m0, s59
	s_nop 0
	global_load_lds_dwordx4 v[156:157], off
	s_waitcnt vmcnt(8)
	s_waitcnt lgkmcnt(0)
	s_barrier
	s_setprio 1
	s_waitcnt lgkmcnt(0)
	v_mfma_f32_16x16x32_bf16 v[62:65], v[140:143], v[196:199], v[62:65]
	v_mfma_f32_16x16x32_bf16 v[58:61], v[152:155], v[196:199], v[58:61]
	v_mfma_f32_16x16x32_bf16 v[46:49], v[140:143], v[204:207], v[46:49]
	v_mfma_f32_16x16x32_bf16 v[42:45], v[152:155], v[204:207], v[42:45]
	v_mfma_f32_16x16x32_bf16 v[30:33], v[140:143], v[212:215], v[30:33]
	v_mfma_f32_16x16x32_bf16 v[26:29], v[152:155], v[212:215], v[26:29]
	v_mfma_f32_16x16x32_bf16 v[14:17], v[140:143], v[224:227], v[14:17]
	v_mfma_f32_16x16x32_bf16 v[10:13], v[152:155], v[224:227], v[10:13]
	v_mfma_f32_16x16x32_bf16 v[62:65], v[148:151], v[200:203], v[62:65]
	v_mfma_f32_16x16x32_bf16 v[58:61], v[160:163], v[200:203], v[58:61]
	v_mfma_f32_16x16x32_bf16 v[46:49], v[148:151], v[208:211], v[46:49]
	v_mfma_f32_16x16x32_bf16 v[42:45], v[160:163], v[208:211], v[42:45]
	v_mfma_f32_16x16x32_bf16 v[30:33], v[148:151], v[216:219], v[30:33]
	v_mfma_f32_16x16x32_bf16 v[26:29], v[160:163], v[216:219], v[26:29]
	v_mfma_f32_16x16x32_bf16 v[14:17], v[148:151], v[228:231], v[14:17]
	v_mfma_f32_16x16x32_bf16 v[10:13], v[160:163], v[228:231], v[10:13]
	s_setprio 0
	s_setprio 1
	v_mfma_f32_16x16x32_bf16 v[54:57], v[164:167], v[196:199], v[54:57]
	v_mfma_f32_16x16x32_bf16 v[50:53], v[188:191], v[196:199], v[50:53]
	v_mfma_f32_16x16x32_bf16 v[38:41], v[164:167], v[204:207], v[38:41]
	v_mfma_f32_16x16x32_bf16 v[34:37], v[188:191], v[204:207], v[34:37]
	v_mfma_f32_16x16x32_bf16 v[22:25], v[164:167], v[212:215], v[22:25]
	v_mfma_f32_16x16x32_bf16 v[18:21], v[188:191], v[212:215], v[18:21]
	v_mfma_f32_16x16x32_bf16 v[6:9], v[164:167], v[224:227], v[6:9]
	v_mfma_f32_16x16x32_bf16 v[2:5], v[188:191], v[224:227], v[2:5]
	v_mfma_f32_16x16x32_bf16 v[54:57], v[184:187], v[200:203], v[54:57]
	v_mfma_f32_16x16x32_bf16 v[50:53], v[192:195], v[200:203], v[50:53]
	v_mfma_f32_16x16x32_bf16 v[38:41], v[184:187], v[208:211], v[38:41]
	v_mfma_f32_16x16x32_bf16 v[34:37], v[192:195], v[208:211], v[34:37]
	v_mfma_f32_16x16x32_bf16 v[22:25], v[184:187], v[216:219], v[22:25]
	v_mfma_f32_16x16x32_bf16 v[18:21], v[192:195], v[216:219], v[18:21]
	v_mfma_f32_16x16x32_bf16 v[6:9], v[184:187], v[228:231], v[6:9]
	v_mfma_f32_16x16x32_bf16 v[2:5], v[192:195], v[228:231], v[2:5]
	s_setprio 0
	s_barrier
	s_add_u32 s42, s42, 0x100
	s_addc_u32 s43, s43, 0
	s_add_u32 s20, s20, 0x100
	s_addc_u32 s21, s21, 0
	s_cmp_ge_u32 s44, s60
	s_mov_b32 s2, s44
	s_cbranch_scc0 .LBB0_384
	s_and_b64 vcc, exec, s[30:31]
	s_cbranch_vccz .LBB0_387
	s_barrier

.LBB0_560:
	s_ashr_i32 s37, s36, 31
	s_lshl_b64 s[2:3], s[36:37], 19
	s_add_u32 s42, s24, s2
	s_addc_u32 s43, s25, s3
	s_and_b64 s[2:3], s[38:39], exec
	s_cselect_b32 s37, s43, s47
	s_cselect_b32 s58, s42, s46
	s_ashr_i32 s35, s34, 31
	s_lshl_b64 s[2:3], s[34:35], 19
	s_add_u32 s44, s10, s2
	s_addc_u32 s45, s11, s3
	s_and_b64 s[2:3], s[38:39], exec
	s_cselect_b32 s35, s45, s41
	s_cselect_b32 s59, s44, s40
	s_add_u32 s60, s40, 0x100
	s_addc_u32 s61, s41, 0
	s_add_u32 s40, s46, 0x40080
	s_addc_u32 s41, s47, 0
	s_mov_b32 s46, -2
.LBB0_561:
	s_add_u32 s2, s40, 0xfffc0080
	s_addc_u32 s3, s41, -1
	s_add_i32 s47, 0, 0x10000
	s_cmp_eq_u32 s46, 12
	s_cselect_b32 s7, s37, s3
	s_cselect_b32 s6, s58, s2
	v_add_u32_e32 v160, s47, v147
	s_cselect_b32 s3, s35, s61
	s_cselect_b32 s2, s59, s60
	s_add_i32 s64, 0, 0x14000
	ds_read_b128 v[164:167], v160
	ds_read_b128 v[184:187], v160 offset:1024
	ds_read_b128 v[188:191], v160 offset:2048
	ds_read_b128 v[192:195], v160 offset:3072
	v_add_u32_e32 v160, s64, v147
	ds_read_b128 v[196:199], v160
	ds_read_b128 v[200:203], v160 offset:1024
	ds_read_b128 v[204:207], v160 offset:2048
	ds_read_b128 v[208:211], v160 offset:3072
	v_lshl_add_u64 v[160:161], s[40:41], 0, v[138:139]
	s_add_i32 m0, s21, 0xc000
	ds_read_b128 v[212:215], v163
	ds_read_b128 v[216:219], v163 offset:1024
	ds_read_b128 v[224:227], v163 offset:2048
	ds_read_b128 v[228:231], v163 offset:3072
	ds_read_b128 v[232:235], v163 offset:4096
	ds_read_b128 v[236:239], v163 offset:5120
	ds_read_b128 v[240:243], v163 offset:6144
	ds_read_b128 v[244:247], v163 offset:7168
	global_load_lds_dwordx4 v[160:161], off
	v_lshl_add_u64 v[160:161], s[40:41], 0, v[136:137]
	s_add_i32 m0, s21, 0xe000
	s_nop 0
	global_load_lds_dwordx4 v[160:161], off
	s_cmp_lg_u32 s46, 0xfffffffe
	s_cbranch_scc1 .Lz0_2
	v_mov_b32_e32 v66, 0
	v_mov_b32_e32 v67, 0
	v_mov_b32_e32 v68, 0
	v_mov_b32_e32 v69, 0
	v_mov_b32_e32 v70, 0
	v_mov_b32_e32 v71, 0
	v_mov_b32_e32 v72, 0
	v_mov_b32_e32 v73, 0
	v_mov_b32_e32 v74, 0
	v_mov_b32_e32 v75, 0
	v_mov_b32_e32 v76, 0
	v_mov_b32_e32 v77, 0
	v_mov_b32_e32 v78, 0
	v_mov_b32_e32 v79, 0
	v_mov_b32_e32 v80, 0
	v_mov_b32_e32 v81, 0
	v_mov_b32_e32 v82, 0
	v_mov_b32_e32 v83, 0
	v_mov_b32_e32 v84, 0
	v_mov_b32_e32 v85, 0
	v_mov_b32_e32 v86, 0
	v_mov_b32_e32 v87, 0
	v_mov_b32_e32 v88, 0
	v_mov_b32_e32 v89, 0
	v_mov_b32_e32 v90, 0
	v_mov_b32_e32 v91, 0
	v_mov_b32_e32 v92, 0
	v_mov_b32_e32 v93, 0
	v_mov_b32_e32 v94, 0
	v_mov_b32_e32 v95, 0
	v_mov_b32_e32 v96, 0
	v_mov_b32_e32 v97, 0
	v_mov_b32_e32 v98, 0
	v_mov_b32_e32 v99, 0
	v_mov_b32_e32 v100, 0
	v_mov_b32_e32 v101, 0
	v_mov_b32_e32 v102, 0
	v_mov_b32_e32 v103, 0
	v_mov_b32_e32 v104, 0
	v_mov_b32_e32 v105, 0
	v_mov_b32_e32 v106, 0
	v_mov_b32_e32 v107, 0
	v_mov_b32_e32 v108, 0
	v_mov_b32_e32 v109, 0
	v_mov_b32_e32 v110, 0
	v_mov_b32_e32 v111, 0
	v_mov_b32_e32 v112, 0
	v_mov_b32_e32 v113, 0
	v_mov_b32_e32 v114, 0
	v_mov_b32_e32 v115, 0
	v_mov_b32_e32 v116, 0
	v_mov_b32_e32 v117, 0
	v_mov_b32_e32 v118, 0
	v_mov_b32_e32 v119, 0
	v_mov_b32_e32 v120, 0
	v_mov_b32_e32 v121, 0
	v_mov_b32_e32 v122, 0
	v_mov_b32_e32 v123, 0
	v_mov_b32_e32 v124, 0
	v_mov_b32_e32 v125, 0
	v_mov_b32_e32 v126, 0
	v_mov_b32_e32 v127, 0
	v_mov_b32_e32 v128, 0
	v_mov_b32_e32 v129, 0
.Lz0_2:
	s_waitcnt vmcnt(8)
	s_waitcnt lgkmcnt(0)
	s_barrier
	s_setprio 1
	s_waitcnt lgkmcnt(0)
	v_mfma_f32_16x16x32_bf16 v[126:129], v[164:167], v[212:215], v[126:129]
	v_mfma_f32_16x16x32_bf16 v[122:125], v[188:191], v[212:215], v[122:125]
	v_mfma_f32_16x16x32_bf16 v[110:113], v[164:167], v[224:227], v[110:113]
	v_mfma_f32_16x16x32_bf16 v[106:109], v[188:191], v[224:227], v[106:109]
	v_mfma_f32_16x16x32_bf16 v[94:97], v[164:167], v[232:235], v[94:97]
	v_mfma_f32_16x16x32_bf16 v[90:93], v[188:191], v[232:235], v[90:93]
	v_mfma_f32_16x16x32_bf16 v[78:81], v[164:167], v[240:243], v[78:81]
	v_mfma_f32_16x16x32_bf16 v[74:77], v[188:191], v[240:243], v[74:77]
	v_mfma_f32_16x16x32_bf16 v[126:129], v[184:187], v[216:219], v[126:129]
	v_mfma_f32_16x16x32_bf16 v[122:125], v[192:195], v[216:219], v[122:125]
	v_mfma_f32_16x16x32_bf16 v[110:113], v[184:187], v[228:231], v[110:113]
	v_mfma_f32_16x16x32_bf16 v[106:109], v[192:195], v[228:231], v[106:109]
	v_mfma_f32_16x16x32_bf16 v[94:97], v[184:187], v[236:239], v[94:97]
	v_mfma_f32_16x16x32_bf16 v[90:93], v[192:195], v[236:239], v[90:93]
	v_mfma_f32_16x16x32_bf16 v[78:81], v[184:187], v[244:247], v[78:81]
	v_mfma_f32_16x16x32_bf16 v[74:77], v[192:195], v[244:247], v[74:77]
	s_setprio 0
	s_setprio 1
	v_mfma_f32_16x16x32_bf16 v[118:121], v[196:199], v[212:215], v[118:121]
	v_mfma_f32_16x16x32_bf16 v[114:117], v[204:207], v[212:215], v[114:117]
	v_mfma_f32_16x16x32_bf16 v[102:105], v[196:199], v[224:227], v[102:105]
	v_mfma_f32_16x16x32_bf16 v[98:101], v[204:207], v[224:227], v[98:101]
	v_mfma_f32_16x16x32_bf16 v[86:89], v[196:199], v[232:235], v[86:89]
	v_mfma_f32_16x16x32_bf16 v[82:85], v[204:207], v[232:235], v[82:85]
	v_mfma_f32_16x16x32_bf16 v[70:73], v[196:199], v[240:243], v[70:73]
	v_mfma_f32_16x16x32_bf16 v[66:69], v[204:207], v[240:243], v[66:69]
	v_mfma_f32_16x16x32_bf16 v[118:121], v[200:203], v[216:219], v[118:121]
	v_mfma_f32_16x16x32_bf16 v[114:117], v[208:211], v[216:219], v[114:117]
	v_mfma_f32_16x16x32_bf16 v[102:105], v[200:203], v[228:231], v[102:105]
	v_mfma_f32_16x16x32_bf16 v[98:101], v[208:211], v[228:231], v[98:101]
	v_mfma_f32_16x16x32_bf16 v[86:89], v[200:203], v[236:239], v[86:89]
	v_mfma_f32_16x16x32_bf16 v[82:85], v[208:211], v[236:239], v[82:85]
	v_mfma_f32_16x16x32_bf16 v[70:73], v[200:203], v[244:247], v[70:73]
	v_mfma_f32_16x16x32_bf16 v[66:69], v[208:211], v[244:247], v[66:69]
	s_setprio 0
	s_barrier
	s_add_i32 s47, s47, s48
	v_lshl_add_u64 v[160:161], s[2:3], 0, v[0:1]
	s_mov_b32 m0, s47
	ds_read_b128 v[212:215], v163 offset:16384
	ds_read_b128 v[216:219], v163 offset:17408
	ds_read_b128 v[224:227], v163 offset:18432
	ds_read_b128 v[228:231], v163 offset:19456
	ds_read_b128 v[232:235], v163 offset:20480
	ds_read_b128 v[236:239], v163 offset:21504
	ds_read_b128 v[240:243], v163 offset:22528
	ds_read_b128 v[244:247], v163 offset:23552
	global_load_lds_dwordx4 v[160:161], off
	s_add_i32 m0, s47, 0x2000
	s_add_u32 s62, s2, 0x40000
	v_lshl_add_u64 v[168:169], s[2:3], 0, v[130:131]
	s_addc_u32 s63, s3, 0
	s_add_i32 s47, s64, s48
	global_load_lds_dwordx4 v[168:169], off
	v_lshl_add_u64 v[248:249], s[62:63], 0, v[0:1]
	s_mov_b32 m0, s47
	v_lshl_add_u64 v[250:251], s[6:7], 0, v[132:133]
	global_load_lds_dwordx4 v[248:249], off
	v_lshl_add_u64 v[248:249], s[62:63], 0, v[130:131]
	s_add_i32 m0, s47, 0x2000
	s_nop 0
	global_load_lds_dwordx4 v[248:249], off
	v_lshl_add_u64 v[248:249], s[6:7], 0, v[134:135]
	s_mov_b32 m0, s21
	s_nop 0
	global_load_lds_dwordx4 v[248:249], off
	s_mov_b32 m0, s50
	s_nop 0
	global_load_lds_dwordx4 v[250:251], off
	s_cmp_lg_u32 s46, 0xfffffffe
	s_cbranch_scc1 .Lz1_2
	v_mov_b32_e32 v2, 0
	v_mov_b32_e32 v3, 0
	v_mov_b32_e32 v4, 0
	v_mov_b32_e32 v5, 0
	v_mov_b32_e32 v6, 0
	v_mov_b32_e32 v7, 0
	v_mov_b32_e32 v8, 0
	v_mov_b32_e32 v9, 0
	v_mov_b32_e32 v10, 0
	v_mov_b32_e32 v11, 0
	v_mov_b32_e32 v12, 0
	v_mov_b32_e32 v13, 0
	v_mov_b32_e32 v14, 0
	v_mov_b32_e32 v15, 0
	v_mov_b32_e32 v16, 0
	v_mov_b32_e32 v17, 0
	v_mov_b32_e32 v18, 0
	v_mov_b32_e32 v19, 0
	v_mov_b32_e32 v20, 0
	v_mov_b32_e32 v21, 0
	v_mov_b32_e32 v22, 0
	v_mov_b32_e32 v23, 0
	v_mov_b32_e32 v24, 0
	v_mov_b32_e32 v25, 0
	v_mov_b32_e32 v26, 0
	v_mov_b32_e32 v27, 0
	v_mov_b32_e32 v28, 0
	v_mov_b32_e32 v29, 0
	v_mov_b32_e32 v30, 0
	v_mov_b32_e32 v31, 0
	v_mov_b32_e32 v32, 0
	v_mov_b32_e32 v33, 0
	v_mov_b32_e32 v34, 0
	v_mov_b32_e32 v35, 0
	v_mov_b32_e32 v36, 0
	v_mov_b32_e32 v37, 0
	v_mov_b32_e32 v38, 0
	v_mov_b32_e32 v39, 0
	v_mov_b32_e32 v40, 0
	v_mov_b32_e32 v41, 0
	v_mov_b32_e32 v42, 0
	v_mov_b32_e32 v43, 0
	v_mov_b32_e32 v44, 0
	v_mov_b32_e32 v45, 0
	v_mov_b32_e32 v46, 0
	v_mov_b32_e32 v47, 0
	v_mov_b32_e32 v48, 0
	v_mov_b32_e32 v49, 0
	v_mov_b32_e32 v50, 0
	v_mov_b32_e32 v51, 0
	v_mov_b32_e32 v52, 0
	v_mov_b32_e32 v53, 0
	v_mov_b32_e32 v54, 0
	v_mov_b32_e32 v55, 0
	v_mov_b32_e32 v56, 0
	v_mov_b32_e32 v57, 0
	v_mov_b32_e32 v58, 0
	v_mov_b32_e32 v59, 0
	v_mov_b32_e32 v60, 0
	v_mov_b32_e32 v61, 0
	v_mov_b32_e32 v62, 0
	v_mov_b32_e32 v63, 0
	v_mov_b32_e32 v64, 0
	v_mov_b32_e32 v65, 0
.Lz1_2:
	s_waitcnt vmcnt(8)
	s_waitcnt lgkmcnt(0)
	s_barrier
	s_setprio 1
	s_waitcnt lgkmcnt(0)
	v_mfma_f32_16x16x32_bf16 v[62:65], v[164:167], v[212:215], v[62:65]
	v_mfma_f32_16x16x32_bf16 v[58:61], v[188:191], v[212:215], v[58:61]
	v_mfma_f32_16x16x32_bf16 v[46:49], v[164:167], v[224:227], v[46:49]
	v_mfma_f32_16x16x32_bf16 v[42:45], v[188:191], v[224:227], v[42:45]
	v_mfma_f32_16x16x32_bf16 v[30:33], v[164:167], v[232:235], v[30:33]
	v_mfma_f32_16x16x32_bf16 v[26:29], v[188:191], v[232:235], v[26:29]
	v_mfma_f32_16x16x32_bf16 v[14:17], v[164:167], v[240:243], v[14:17]
	v_mfma_f32_16x16x32_bf16 v[10:13], v[188:191], v[240:243], v[10:13]
	v_mfma_f32_16x16x32_bf16 v[62:65], v[184:187], v[216:219], v[62:65]
	v_mfma_f32_16x16x32_bf16 v[58:61], v[192:195], v[216:219], v[58:61]
	v_mfma_f32_16x16x32_bf16 v[46:49], v[184:187], v[228:231], v[46:49]
	v_mfma_f32_16x16x32_bf16 v[42:45], v[192:195], v[228:231], v[42:45]
	v_mfma_f32_16x16x32_bf16 v[30:33], v[184:187], v[236:239], v[30:33]
	v_mfma_f32_16x16x32_bf16 v[26:29], v[192:195], v[236:239], v[26:29]
	v_mfma_f32_16x16x32_bf16 v[14:17], v[184:187], v[244:247], v[14:17]
	v_mfma_f32_16x16x32_bf16 v[10:13], v[192:195], v[244:247], v[10:13]
	s_setprio 0
	s_setprio 1
	v_mfma_f32_16x16x32_bf16 v[54:57], v[196:199], v[212:215], v[54:57]
	v_mfma_f32_16x16x32_bf16 v[50:53], v[204:207], v[212:215], v[50:53]
	v_mfma_f32_16x16x32_bf16 v[38:41], v[196:199], v[224:227], v[38:41]
	v_mfma_f32_16x16x32_bf16 v[34:37], v[204:207], v[224:227], v[34:37]
	v_mfma_f32_16x16x32_bf16 v[22:25], v[196:199], v[232:235], v[22:25]
	v_mfma_f32_16x16x32_bf16 v[18:21], v[204:207], v[232:235], v[18:21]
	v_mfma_f32_16x16x32_bf16 v[6:9], v[196:199], v[240:243], v[6:9]
	v_mfma_f32_16x16x32_bf16 v[2:5], v[204:207], v[240:243], v[2:5]
	v_mfma_f32_16x16x32_bf16 v[54:57], v[200:203], v[216:219], v[54:57]
	v_mfma_f32_16x16x32_bf16 v[50:53], v[208:211], v[216:219], v[50:53]
	v_mfma_f32_16x16x32_bf16 v[38:41], v[200:203], v[228:231], v[38:41]
	v_mfma_f32_16x16x32_bf16 v[34:37], v[208:211], v[228:231], v[34:37]
	v_mfma_f32_16x16x32_bf16 v[22:25], v[200:203], v[236:239], v[22:25]
	v_mfma_f32_16x16x32_bf16 v[18:21], v[208:211], v[236:239], v[18:21]
	v_mfma_f32_16x16x32_bf16 v[6:9], v[200:203], v[244:247], v[6:9]
	v_mfma_f32_16x16x32_bf16 v[2:5], v[208:211], v[244:247], v[2:5]
	s_setprio 0
	s_barrier
	s_add_i32 s47, 0, 0x18000
	s_add_i32 s62, 0, 0x1c000
	v_add_u32_e32 v192, s47, v147
	v_add_u32_e32 v208, s62, v147
	ds_read_b128 v[164:167], v192
	ds_read_b128 v[184:187], v192 offset:1024
	ds_read_b128 v[188:191], v192 offset:2048
	ds_read_b128 v[192:195], v192 offset:3072
	ds_read_b128 v[196:199], v208
	ds_read_b128 v[200:203], v208 offset:1024
	ds_read_b128 v[204:207], v208 offset:2048
	ds_read_b128 v[208:211], v208 offset:3072
	s_add_u32 s6, s6, 0x40000
	s_addc_u32 s7, s7, 0
	s_mov_b32 m0, s51
	v_lshl_add_u64 v[252:253], s[6:7], 0, v[134:135]
	ds_read_b128 v[212:215], v163 offset:32768
	ds_read_b128 v[216:219], v163 offset:33792
	ds_read_b128 v[224:227], v163 offset:34816
	ds_read_b128 v[228:231], v163 offset:35840
	ds_read_b128 v[232:235], v163 offset:36864
	ds_read_b128 v[236:239], v163 offset:37888
	ds_read_b128 v[240:243], v163 offset:38912
	ds_read_b128 v[244:247], v163 offset:39936
	global_load_lds_dwordx4 v[252:253], off
	v_lshl_add_u64 v[252:253], s[6:7], 0, v[132:133]
	s_mov_b32 m0, s52
	s_nop 0
	global_load_lds_dwordx4 v[252:253], off
	s_waitcnt vmcnt(8)
	s_waitcnt lgkmcnt(0)
	s_barrier
	s_setprio 1
	s_waitcnt lgkmcnt(0)
	v_mfma_f32_16x16x32_bf16 v[126:129], v[164:167], v[212:215], v[126:129]
	v_mfma_f32_16x16x32_bf16 v[122:125], v[188:191], v[212:215], v[122:125]
	v_mfma_f32_16x16x32_bf16 v[110:113], v[164:167], v[224:227], v[110:113]
	v_mfma_f32_16x16x32_bf16 v[106:109], v[188:191], v[224:227], v[106:109]
	v_mfma_f32_16x16x32_bf16 v[94:97], v[164:167], v[232:235], v[94:97]
	v_mfma_f32_16x16x32_bf16 v[90:93], v[188:191], v[232:235], v[90:93]
	v_mfma_f32_16x16x32_bf16 v[78:81], v[164:167], v[240:243], v[78:81]
	v_mfma_f32_16x16x32_bf16 v[74:77], v[188:191], v[240:243], v[74:77]
	v_mfma_f32_16x16x32_bf16 v[126:129], v[184:187], v[216:219], v[126:129]
	v_mfma_f32_16x16x32_bf16 v[122:125], v[192:195], v[216:219], v[122:125]
	v_mfma_f32_16x16x32_bf16 v[110:113], v[184:187], v[228:231], v[110:113]
	v_mfma_f32_16x16x32_bf16 v[106:109], v[192:195], v[228:231], v[106:109]
	v_mfma_f32_16x16x32_bf16 v[94:97], v[184:187], v[236:239], v[94:97]
	v_mfma_f32_16x16x32_bf16 v[90:93], v[192:195], v[236:239], v[90:93]
	v_mfma_f32_16x16x32_bf16 v[78:81], v[184:187], v[244:247], v[78:81]
	v_mfma_f32_16x16x32_bf16 v[74:77], v[192:195], v[244:247], v[74:77]
	s_setprio 0
	s_setprio 1
	v_mfma_f32_16x16x32_bf16 v[118:121], v[196:199], v[212:215], v[118:121]
	v_mfma_f32_16x16x32_bf16 v[114:117], v[204:207], v[212:215], v[114:117]
	v_mfma_f32_16x16x32_bf16 v[102:105], v[196:199], v[224:227], v[102:105]
	v_mfma_f32_16x16x32_bf16 v[98:101], v[204:207], v[224:227], v[98:101]
	v_mfma_f32_16x16x32_bf16 v[86:89], v[196:199], v[232:235], v[86:89]
	v_mfma_f32_16x16x32_bf16 v[82:85], v[204:207], v[232:235], v[82:85]
	v_mfma_f32_16x16x32_bf16 v[70:73], v[196:199], v[240:243], v[70:73]
	v_mfma_f32_16x16x32_bf16 v[66:69], v[204:207], v[240:243], v[66:69]
	v_mfma_f32_16x16x32_bf16 v[118:121], v[200:203], v[216:219], v[118:121]
	v_mfma_f32_16x16x32_bf16 v[114:117], v[208:211], v[216:219], v[114:117]
	v_mfma_f32_16x16x32_bf16 v[102:105], v[200:203], v[228:231], v[102:105]
	v_mfma_f32_16x16x32_bf16 v[98:101], v[208:211], v[228:231], v[98:101]
	v_mfma_f32_16x16x32_bf16 v[86:89], v[200:203], v[236:239], v[86:89]
	v_mfma_f32_16x16x32_bf16 v[82:85], v[208:211], v[236:239], v[82:85]
	v_mfma_f32_16x16x32_bf16 v[70:73], v[200:203], v[244:247], v[70:73]
	v_mfma_f32_16x16x32_bf16 v[66:69], v[208:211], v[244:247], v[66:69]
	s_setprio 0
	s_barrier
	s_add_i32 s6, s47, s48
	v_lshl_add_u64 v[160:161], v[160:161], 0, s[12:13]
	s_mov_b32 m0, s6
	ds_read_b128 v[212:215], v163 offset:49152
	ds_read_b128 v[216:219], v163 offset:50176
	ds_read_b128 v[224:227], v163 offset:51200
	ds_read_b128 v[228:231], v163 offset:52224
	ds_read_b128 v[232:235], v163 offset:53248
	ds_read_b128 v[236:239], v163 offset:54272
	ds_read_b128 v[240:243], v163 offset:55296
	ds_read_b128 v[244:247], v163 offset:56320
	global_load_lds_dwordx4 v[160:161], off
	s_add_i32 m0, s6, 0x2000
	s_add_u32 s2, s2, 0x40080
	v_lshl_add_u64 v[160:161], v[168:169], 0, s[12:13]
	s_addc_u32 s3, s3, 0
	s_add_i32 s6, s62, s48
	global_load_lds_dwordx4 v[160:161], off
	v_lshl_add_u64 v[160:161], s[2:3], 0, v[0:1]
	s_mov_b32 m0, s6
	s_nop 0
	global_load_lds_dwordx4 v[160:161], off
	v_lshl_add_u64 v[160:161], s[2:3], 0, v[130:131]
	s_add_i32 m0, s6, 0x2000
	s_nop 0
	global_load_lds_dwordx4 v[160:161], off
	v_lshl_add_u64 v[160:161], v[248:249], 0, s[12:13]
	s_mov_b32 m0, s54
	s_nop 0
	global_load_lds_dwordx4 v[160:161], off
	v_lshl_add_u64 v[160:161], v[250:251], 0, s[12:13]
	s_mov_b32 m0, s55
	s_nop 0
	global_load_lds_dwordx4 v[160:161], off
	s_waitcnt vmcnt(8)
	s_waitcnt lgkmcnt(0)
	s_barrier
	s_setprio 1
	s_waitcnt lgkmcnt(0)
	v_mfma_f32_16x16x32_bf16 v[62:65], v[164:167], v[212:215], v[62:65]
	v_mfma_f32_16x16x32_bf16 v[58:61], v[188:191], v[212:215], v[58:61]
	v_mfma_f32_16x16x32_bf16 v[46:49], v[164:167], v[224:227], v[46:49]
	v_mfma_f32_16x16x32_bf16 v[42:45], v[188:191], v[224:227], v[42:45]
	v_mfma_f32_16x16x32_bf16 v[30:33], v[164:167], v[232:235], v[30:33]
	v_mfma_f32_16x16x32_bf16 v[26:29], v[188:191], v[232:235], v[26:29]
	v_mfma_f32_16x16x32_bf16 v[14:17], v[164:167], v[240:243], v[14:17]
	v_mfma_f32_16x16x32_bf16 v[10:13], v[188:191], v[240:243], v[10:13]
	v_mfma_f32_16x16x32_bf16 v[62:65], v[184:187], v[216:219], v[62:65]
	v_mfma_f32_16x16x32_bf16 v[58:61], v[192:195], v[216:219], v[58:61]
	v_mfma_f32_16x16x32_bf16 v[46:49], v[184:187], v[228:231], v[46:49]
	v_mfma_f32_16x16x32_bf16 v[42:45], v[192:195], v[228:231], v[42:45]
	v_mfma_f32_16x16x32_bf16 v[30:33], v[184:187], v[236:239], v[30:33]
	v_mfma_f32_16x16x32_bf16 v[26:29], v[192:195], v[236:239], v[26:29]
	v_mfma_f32_16x16x32_bf16 v[14:17], v[184:187], v[244:247], v[14:17]
	v_mfma_f32_16x16x32_bf16 v[10:13], v[192:195], v[244:247], v[10:13]
	s_setprio 0
	s_setprio 1
	v_mfma_f32_16x16x32_bf16 v[54:57], v[196:199], v[212:215], v[54:57]
	v_mfma_f32_16x16x32_bf16 v[50:53], v[204:207], v[212:215], v[50:53]
	v_mfma_f32_16x16x32_bf16 v[38:41], v[196:199], v[224:227], v[38:41]
	v_mfma_f32_16x16x32_bf16 v[34:37], v[204:207], v[224:227], v[34:37]
	v_mfma_f32_16x16x32_bf16 v[22:25], v[196:199], v[232:235], v[22:25]
	v_mfma_f32_16x16x32_bf16 v[18:21], v[204:207], v[232:235], v[18:21]
	v_mfma_f32_16x16x32_bf16 v[6:9], v[196:199], v[240:243], v[6:9]
	v_mfma_f32_16x16x32_bf16 v[2:5], v[204:207], v[240:243], v[2:5]
	v_mfma_f32_16x16x32_bf16 v[54:57], v[200:203], v[216:219], v[54:57]
	v_mfma_f32_16x16x32_bf16 v[50:53], v[208:211], v[216:219], v[50:53]
	v_mfma_f32_16x16x32_bf16 v[38:41], v[200:203], v[228:231], v[38:41]
	v_mfma_f32_16x16x32_bf16 v[34:37], v[208:211], v[228:231], v[34:37]
	v_mfma_f32_16x16x32_bf16 v[22:25], v[200:203], v[236:239], v[22:25]
	v_mfma_f32_16x16x32_bf16 v[18:21], v[208:211], v[236:239], v[18:21]
	v_mfma_f32_16x16x32_bf16 v[6:9], v[200:203], v[244:247], v[6:9]
	v_mfma_f32_16x16x32_bf16 v[2:5], v[208:211], v[244:247], v[2:5]
	s_setprio 0
	s_barrier
	s_add_i32 s46, s46, 2
	s_add_u32 s60, s60, 0x100
	s_addc_u32 s61, s61, 0
	s_add_u32 s40, s40, 0x100
	s_addc_u32 s41, s41, 0
	s_cmp_gt_u32 s46, 13
	s_cbranch_scc0 .LBB0_561
	s_and_b64 vcc, exec, s[30:31]
	s_cbranch_vccz .LBB0_564
	s_barrier
